# Up GEMM K-loop: LDS-DMA loads use scalar-base addressing, A-fragment LDS addresses from one persistent VGPR (no VALU in load segments)
# speedup vs baseline: 1.0062x; 1.0025x over previous
; #define PG8_STAGE(bufoff, gbase, voff) do { _Pragma("unroll") for (int _i = 0; _i < 2; ++_i) \
;         __builtin_amdgcn_global_load_lds((const unsigned*)((const char*)(gbase) + (voff)[_i]), (LAS unsigned*)(lds + (bufoff) + ldsw + _i * 8192), 16, 0, 0); } while (0)
; #define PG8_WAIT_V(n) asm volatile("s_waitcnt vmcnt(" #n ")" ::: "memory")
; #define PG8_BAR __builtin_amdgcn_s_barrier()
;     __device__ __forceinline__ void init(f32x4 (&acc)[2][2][4][2], const pg8::Unit&, int, int, int, int) const { acc_zero(acc); }
; template <class Epi, class Sched>
; __device__ __forceinline__ void gemm_phase(LAS unsigned char* lds, const Gemm g, const Sched& S, const Epi& E) {
;     ...
;     const int wid = __builtin_amdgcn_readfirstlane(tid >> 6), lane = tid & 63, wr = wid >> 2, wc = wid & 3, fr = lane & 15, fq = lane >> 4;
;     const int nt = g.K / BK;
;     unsigned voffA[2], voffB[2];
; #pragma unroll
;     for (int i = 0; i < 2; ++i) { int R, C; stage_rc(tid * 16 + i * 8192, R, C); const int Rb = Epi::PERM ? ((R & ~31) + perm32(R & 31)) : R;
;         voffA[i] = (unsigned)(R * g.lda + C) * 2u; voffB[i] = (unsigned)(Rb * g.ldb + C) * 2u; }
;     asm volatile("" : "+v"(voffA[0]), "+v"(voffA[1]), "+v"(voffB[0]), "+v"(voffB[1]));
;     const size_t kstep = (size_t)(BK * 2);
;     const size_t hstepA = (size_t)HALF * g.lda * 2, hstepB = (size_t)HALF * g.ldb * 2;
;     const size_t tstepA = 2 * hstepA, tstepB = 2 * hstepB;
;     const unsigned ldsw = (unsigned)wid * 1024u;
;     const int aoff = lds_byte(wr * 64 + fr, fq * 8), boff = lds_byte(wc * 32 + fr, fq * 8);
;     ...
;     Unit cur, nxt; int ui = 0;
;     if (!S.next(0, cur)) return;
;     f32x4 acc[2][2][4][2];
;     E.init(acc, cur, wr, wc, fr, fq);
;     bf16x8 At[4][2], B0[2][2], B1[2][2];
;     const char* cA = (const char*)g.A + (size_t)cur.pm * tstepA + (size_t)cur.pn * g.a_pn_off * 2; const char* cB = (const char*)g.Bt + (size_t)cur.pn * tstepB;
;     PG8_STAGE(PG8_SB(0, 0), cB, voffB); PG8_STAGE(PG8_SB(0, 1), cB + hstepB, voffB); PG8_STAGE(PG8_SA(0, 0), cA, voffA); PG8_STAGE(PG8_SA(0, 1), cA + hstepA, voffA);
;     if (wr == 1) PG8_BAR;
;     PG8_WAIT_V(2); PG8_BAR;
;     PG8_STAGE(PG8_SB(1, 0), cB + kstep, voffB); PG8_STAGE(PG8_SA(1, 0), cA + kstep, voffA); PG8_STAGE(PG8_SB(1, 1), cB + hstepB + kstep, voffB);
;     PG8_WAIT_V(6); PG8_BAR;
.LBB0_226:
	v_and_b32_e32 v1, 15, v2
	v_lshrrev_b32_e32 v2, 1, v2
	v_and_b32_e32 v12, 24, v2
	v_readlane_b32 s48, v248, 9
	v_lshlrev_b32_e32 v2, 1, v12
	v_lshlrev_b32_e32 v13, 2, v1
	v_mov_b32_e32 v173, v0
	v_readlane_b32 s49, v248, 10
	s_and_b32 s20, s20, 3
	v_lshl_or_b32 v2, v1, 6, v2
	s_lshl_b32 s21, s19, 13
	v_and_b32_e32 v3, 32, v13
	v_lshl_add_u64 v[4:5], s[48:49], 0, v[172:173]
	v_mov_b32_e32 v193, v0
	v_readlane_b32 s14, v250, 5
	v_bitop3_b32 v14, v2, s21, v3 bitop3:0xde
	s_lshl_b32 s21, s20, 12
	v_lshl_add_u64 v[6:7], s[48:49], 0, v[192:193]
	v_mov_b32_e32 v171, v0
	v_readlane_b32 s15, v250, 6
	v_bitop3_b32 v207, v2, s21, v3 bitop3:0xde
	v_add_u32_e32 v246, 0x10000, v207
	s_add_i32 m0, s9, 0x18000
	v_lshl_add_u64 v[2:3], v[4:5], 0, s[62:63]
	v_lshl_add_u64 v[8:9], s[14:15], 0, v[170:171]
	v_mov_b32_e32 v191, v0
	s_waitcnt vmcnt(2)
	s_barrier
	global_load_lds_dwordx4 v[2:3], off
	v_lshl_add_u64 v[2:3], v[6:7], 0, s[62:63]
	s_add_i32 m0, s9, 0x1a000
	s_add_i32 s31, s9, 0x8000
	v_lshl_add_u64 v[10:11], s[14:15], 0, v[190:191]
	global_load_lds_dwordx4 v[2:3], off
	v_lshl_add_u64 v[2:3], v[8:9], 0, s[62:63]
	s_mov_b32 m0, s31
	s_add_i32 s34, s9, 0xa000
	v_readlane_b32 s12, v248, 11
	global_load_lds_dwordx4 v[2:3], off
	v_lshl_add_u64 v[2:3], v[10:11], 0, s[62:63]
	s_mov_b32 m0, s34
	v_readlane_b32 s13, v248, 12
	global_load_lds_dwordx4 v[2:3], off
	s_add_i32 m0, s9, 0x1c000
	v_lshl_add_u64 v[2:3], s[12:13], 0, v[172:173]
	global_load_lds_dwordx4 v[2:3], off
	v_lshl_add_u64 v[2:3], s[12:13], 0, v[192:193]
	s_add_i32 m0, s9, 0x1e000
	s_cmpk_lt_u32 s18, 0x100
	global_load_lds_dwordx4 v[2:3], off
	s_cselect_b64 s[72:73], -1, 0
	s_cmpk_gt_u32 s18, 0xff
	s_cselect_b64 s[74:75], -1, 0
	s_and_b32 s21, s18, 0xffffff00
	s_lshl_b32 s35, s19, 10
	s_lshl_b32 s36, s20, 8
	s_cmp_lg_u32 s19, 1
	v_lshl_or_b32 v206, s19, 6, v1
	s_cselect_b64 s[18:19], -1, 0
	v_cndmask_b32_e64 v4, 0, -1, s[18:19]
	s_and_b64 s[18:19], s[18:19], exec
	s_cselect_b32 s18, 0, 0x800
	s_add_i32 s21, s21, 0
	s_add_i32 s21, s21, 0x20000
	v_readlane_b32 s12, v249, 25
	v_add_u32_e32 v208, s21, v13
	s_add_i32 s21, s12, s35
	v_lshlrev_b32_e32 v2, 7, v1
	v_lshlrev_b32_e32 v4, 11, v4
	s_or_b32 s19, s36, s35
	s_add_i32 s21, s21, s36
	v_lshlrev_b32_e32 v5, 2, v12
	s_waitcnt vmcnt(6)
	v_sub_u32_e64 v3, v1, 14 clamp
	s_xor_b32 s19, s19, 0x400
	v_add3_u32 v209, s21, v2, v5
	v_add_u32_e32 v2, s12, v4
	s_add_i32 s18, s12, s18
	v_cmp_lt_u32_e64 s[66:67], 13, v1
	v_lshlrev_b32_e32 v3, 7, v3
	v_add_u32_e32 v2, s19, v2
	s_add_i32 s18, s18, s19
	v_readlane_b32 s12, v250, 3
	s_mov_b32 s41, 0
	v_cmp_eq_u32_e64 s[68:69], 0, v1
	v_cmp_gt_u32_e64 s[76:77], 2, v1
	s_and_b64 s[78:79], s[66:67], s[0:1]
	v_add_u32_e32 v217, 0xfffff900, v209
	v_add_u32_e32 v218, 0xfffff910, v209
	v_add3_u32 v219, v2, v3, v5
	v_add3_u32 v220, s18, v3, v5
	v_lshl_or_b32 v221, s20, 5, v12
	v_add_u32_e32 v222, 0, v14
	v_readlane_b32 s42, v250, 0
	s_mov_b32 s40, s12
	s_mov_b64 s[20:21], s[48:49]
	s_mov_b64 s[18:19], s[14:15]
	s_mov_b32 s14, 0x3fb8aa3b
	s_barrier
	v_readlane_b32 s13, v250, 4
	s_branch .LBB0_229

; #define PG8_STAGE(bufoff, gbase, voff) do { _Pragma("unroll") for (int _i = 0; _i < 2; ++_i) \
;         __builtin_amdgcn_global_load_lds((const unsigned*)((const char*)(gbase) + (voff)[_i]), (LAS unsigned*)(lds + (bufoff) + ldsw + _i * 8192), 16, 0, 0); } while (0)
; #define PG8_LDA(dst, b, h) do { _Pragma("unroll") for (int m = 0; m < 4; ++m) _Pragma("unroll") for (int k = 0; k < 2; ++k) dst[m][k] = *(const LAS bf16x8*)(lds + PG8_SA(b, h) + aoff + m * 2048 + k * 1024); } while (0)
; #define PG8_LDB(dst, b, h) do { _Pragma("unroll") for (int n = 0; n < 2; ++n) _Pragma("unroll") for (int k = 0; k < 2; ++k) dst[n][k] = *(const LAS bf16x8*)(lds + PG8_SB(b, h) + boff + n * 2048 + k * 1024); } while (0)
; #define PG8_MMA(ai, bj, At, Bt) do { __builtin_amdgcn_s_setprio(1); _Pragma("unroll") for (int m = 0; m < 4; ++m) _Pragma("unroll") for (int n = 0; n < 2; ++n) _Pragma("unroll") for (int k = 0; k < 2; ++k) \
;         acc[ai][bj][m][n] = __builtin_amdgcn_mfma_f32_16x16x32_bf16(Bt[n][k], At[m][k], acc[ai][bj][m][n], 0, 0, 0); __builtin_amdgcn_s_setprio(0); } while (0)
; #define PG8_WAIT_V(n) asm volatile("s_waitcnt vmcnt(" #n ")" ::: "memory")
; #define PG8_WAIT_L(n) asm volatile("s_waitcnt lgkmcnt(" #n ")" ::: "memory")
; #define PG8_BAR __builtin_amdgcn_s_barrier()
; #define PG8_SCHED __builtin_amdgcn_sched_barrier(0)
; template <class Epi, class Sched>
; __device__ __forceinline__ void gemm_phase(LAS unsigned char* lds, const Gemm g, const Sched& S, const Epi& E) {
;     ...
;         for (int t = 0; t < nt; t += 2) {
;             const bool last = (t == nt - 2);
;             const char* a1 = cA + (size_t)(t + 1) * kstep;
;             const char* a2 = last ? nA : cA + (size_t)(t + 2) * kstep; const char* b2 = last ? nB : cB + (size_t)(t + 2) * kstep;
;             const char* a3 = a2 + kstep; const char* b3 = b2 + kstep;
;             PG8_LDB(B0, 0, 0); PG8_LDB(B1, 0, 1); PG8_SCHED; PG8_LDA(At, 0, 0); PG8_STAGE(PG8_SA(1, 1), a1 + hstepA, voffA);
;             PG8_WAIT_V(8); PG8_WAIT_L(0); PG8_BAR; PG8_MMA(0, 0, At, B0); PG8_MMA(0, 1, At, B1); PG8_BAR; PG8_SCHED;
;             PG8_LDA(At, 0, 1); PG8_STAGE(PG8_SB(0, 0), b2, voffB); PG8_STAGE(PG8_SB(0, 1), b2 + hstepB, voffB); PG8_STAGE(PG8_SA(0, 0), a2, voffA);
;             PG8_WAIT_V(8); PG8_WAIT_L(0); PG8_BAR; PG8_MMA(1, 0, At, B0); PG8_MMA(1, 1, At, B1); PG8_BAR; PG8_SCHED;
.LBB0_232:
	s_add_u32 s20, s18, 0xfffc0080
	s_addc_u32 s21, s19, -1
	s_add_i32 s88, 0, 0x10000
	s_cmp_eq_u32 s83, 12
	s_cselect_b32 s21, s43, s21
	s_cselect_b32 s20, s48, s20
	s_cselect_b32 s87, s49, s81
	s_cselect_b32 s86, s53, s54
	s_add_i32 s90, 0, 0x14000
	s_add_u32 s100, s20, 0x80
	s_addc_u32 s101, s21, 0
	ds_read_b128 v[130:133], v246
	ds_read_b128 v[134:137], v246 offset:1024
	ds_read_b128 v[138:141], v246 offset:2048
	ds_read_b128 v[142:145], v246 offset:3072
	ds_read_b128 v[146:149], v246 offset:16384
	ds_read_b128 v[150:153], v246 offset:17408
	ds_read_b128 v[154:157], v246 offset:18432
	ds_read_b128 v[158:161], v246 offset:19456
	s_add_i32 m0, s9, 0xc000
	ds_read_b128 v[162:165], v222
	ds_read_b128 v[166:169], v222 offset:1024
	ds_read_b128 v[194:197], v222 offset:2048
	ds_read_b128 v[198:201], v222 offset:3072
	ds_read_b128 v[202:205], v222 offset:4096
	ds_read_b128 v[224:227], v222 offset:5120
	ds_read_b128 v[228:231], v222 offset:6144
	ds_read_b128 v[232:235], v222 offset:7168
	global_load_lds_dwordx4 v170, s[18:19]
	s_add_i32 m0, s9, 0xe000
	s_nop 0
	global_load_lds_dwordx4 v190, s[18:19]
	s_waitcnt vmcnt(8)
	s_waitcnt lgkmcnt(0)
	s_barrier
	s_setprio 1
	s_waitcnt lgkmcnt(0)
	v_mfma_f32_16x16x32_bf16 v[126:129], v[130:133], v[162:165], v[126:129]
	v_mfma_f32_16x16x32_bf16 v[118:121], v[138:141], v[162:165], v[118:121]
	v_mfma_f32_16x16x32_bf16 v[110:113], v[130:133], v[194:197], v[110:113]
	v_mfma_f32_16x16x32_bf16 v[102:105], v[138:141], v[194:197], v[102:105]
	v_mfma_f32_16x16x32_bf16 v[94:97], v[130:133], v[202:205], v[94:97]
	v_mfma_f32_16x16x32_bf16 v[86:89], v[138:141], v[202:205], v[86:89]
	v_mfma_f32_16x16x32_bf16 v[78:81], v[130:133], v[228:231], v[78:81]
	v_mfma_f32_16x16x32_bf16 v[70:73], v[138:141], v[228:231], v[70:73]
	v_mfma_f32_16x16x32_bf16 v[126:129], v[134:137], v[166:169], v[126:129]
	v_mfma_f32_16x16x32_bf16 v[118:121], v[142:145], v[166:169], v[118:121]
	v_mfma_f32_16x16x32_bf16 v[110:113], v[134:137], v[198:201], v[110:113]
	v_mfma_f32_16x16x32_bf16 v[102:105], v[142:145], v[198:201], v[102:105]
	v_mfma_f32_16x16x32_bf16 v[94:97], v[134:137], v[224:227], v[94:97]
	v_mfma_f32_16x16x32_bf16 v[86:89], v[142:145], v[224:227], v[86:89]
	v_mfma_f32_16x16x32_bf16 v[78:81], v[134:137], v[232:235], v[78:81]
	v_mfma_f32_16x16x32_bf16 v[70:73], v[142:145], v[232:235], v[70:73]
	s_setprio 0
	s_setprio 1
	v_mfma_f32_16x16x32_bf16 v[122:125], v[146:149], v[162:165], v[122:125]
	v_mfma_f32_16x16x32_bf16 v[114:117], v[154:157], v[162:165], v[114:117]
	v_mfma_f32_16x16x32_bf16 v[106:109], v[146:149], v[194:197], v[106:109]
	v_mfma_f32_16x16x32_bf16 v[98:101], v[154:157], v[194:197], v[98:101]
	v_mfma_f32_16x16x32_bf16 v[90:93], v[146:149], v[202:205], v[90:93]
	v_mfma_f32_16x16x32_bf16 v[82:85], v[154:157], v[202:205], v[82:85]
	v_mfma_f32_16x16x32_bf16 v[74:77], v[146:149], v[228:231], v[74:77]
	v_mfma_f32_16x16x32_bf16 v[66:69], v[154:157], v[228:231], v[66:69]
	v_mfma_f32_16x16x32_bf16 v[122:125], v[150:153], v[166:169], v[122:125]
	v_mfma_f32_16x16x32_bf16 v[114:117], v[158:161], v[166:169], v[114:117]
	v_mfma_f32_16x16x32_bf16 v[106:109], v[150:153], v[198:201], v[106:109]
	v_mfma_f32_16x16x32_bf16 v[98:101], v[158:161], v[198:201], v[98:101]
	v_mfma_f32_16x16x32_bf16 v[90:93], v[150:153], v[224:227], v[90:93]
	v_mfma_f32_16x16x32_bf16 v[82:85], v[158:161], v[224:227], v[82:85]
	v_mfma_f32_16x16x32_bf16 v[74:77], v[150:153], v[232:235], v[74:77]
	v_mfma_f32_16x16x32_bf16 v[66:69], v[158:161], v[232:235], v[66:69]
	s_setprio 0
	s_barrier
	s_add_i32 s88, s88, s8
	s_mov_b32 m0, s88
	ds_read_b128 v[162:165], v222 offset:16384
	ds_read_b128 v[166:169], v222 offset:17408
	ds_read_b128 v[194:197], v222 offset:18432
	ds_read_b128 v[198:201], v222 offset:19456
	ds_read_b128 v[202:205], v222 offset:20480
	ds_read_b128 v[224:227], v222 offset:21504
	ds_read_b128 v[228:231], v222 offset:22528
	ds_read_b128 v[232:235], v222 offset:23552
	global_load_lds_dwordx4 v172, s[86:87]
	s_add_i32 m0, s88, 0x2000
	s_add_u32 s88, s86, 0x40000
	s_addc_u32 s89, s87, 0
	s_add_i32 s90, s90, s8
	global_load_lds_dwordx4 v192, s[86:87]
	s_mov_b32 m0, s90
	s_nop 0
	global_load_lds_dwordx4 v172, s[88:89]
	s_add_i32 m0, s90, 0x2000
	s_nop 0
	global_load_lds_dwordx4 v192, s[88:89]
	s_mov_b32 m0, s9
	s_nop 0
	global_load_lds_dwordx4 v170, s[20:21]
	s_mov_b32 m0, s28
	s_nop 0
	global_load_lds_dwordx4 v190, s[20:21]
	s_waitcnt vmcnt(8)
	s_waitcnt lgkmcnt(0)
	s_barrier
	s_setprio 1
	s_waitcnt lgkmcnt(0)
	v_mfma_f32_16x16x32_bf16 v[62:65], v[130:133], v[162:165], v[62:65]
	v_mfma_f32_16x16x32_bf16 v[54:57], v[138:141], v[162:165], v[54:57]
	v_mfma_f32_16x16x32_bf16 v[46:49], v[130:133], v[194:197], v[46:49]
	v_mfma_f32_16x16x32_bf16 v[38:41], v[138:141], v[194:197], v[38:41]
	v_mfma_f32_16x16x32_bf16 v[30:33], v[130:133], v[202:205], v[30:33]
	v_mfma_f32_16x16x32_bf16 v[22:25], v[138:141], v[202:205], v[22:25]
	v_mfma_f32_16x16x32_bf16 v[14:17], v[130:133], v[228:231], v[14:17]
	v_mfma_f32_16x16x32_bf16 v[6:9], v[138:141], v[228:231], v[6:9]
	v_mfma_f32_16x16x32_bf16 v[62:65], v[134:137], v[166:169], v[62:65]
	v_mfma_f32_16x16x32_bf16 v[54:57], v[142:145], v[166:169], v[54:57]
	v_mfma_f32_16x16x32_bf16 v[46:49], v[134:137], v[198:201], v[46:49]
	v_mfma_f32_16x16x32_bf16 v[38:41], v[142:145], v[198:201], v[38:41]
	v_mfma_f32_16x16x32_bf16 v[30:33], v[134:137], v[224:227], v[30:33]
	v_mfma_f32_16x16x32_bf16 v[22:25], v[142:145], v[224:227], v[22:25]
	v_mfma_f32_16x16x32_bf16 v[14:17], v[134:137], v[232:235], v[14:17]
	v_mfma_f32_16x16x32_bf16 v[6:9], v[142:145], v[232:235], v[6:9]
	s_setprio 0
	s_setprio 1
	v_mfma_f32_16x16x32_bf16 v[58:61], v[146:149], v[162:165], v[58:61]
	v_mfma_f32_16x16x32_bf16 v[50:53], v[154:157], v[162:165], v[50:53]
	v_mfma_f32_16x16x32_bf16 v[42:45], v[146:149], v[194:197], v[42:45]
	v_mfma_f32_16x16x32_bf16 v[34:37], v[154:157], v[194:197], v[34:37]
	v_mfma_f32_16x16x32_bf16 v[26:29], v[146:149], v[202:205], v[26:29]
	v_mfma_f32_16x16x32_bf16 v[18:21], v[154:157], v[202:205], v[18:21]
	v_mfma_f32_16x16x32_bf16 v[10:13], v[146:149], v[228:231], v[10:13]
	v_mfma_f32_16x16x32_bf16 v[2:5], v[154:157], v[228:231], v[2:5]
	v_mfma_f32_16x16x32_bf16 v[58:61], v[150:153], v[166:169], v[58:61]
	v_mfma_f32_16x16x32_bf16 v[50:53], v[158:161], v[166:169], v[50:53]
	v_mfma_f32_16x16x32_bf16 v[42:45], v[150:153], v[198:201], v[42:45]
	v_mfma_f32_16x16x32_bf16 v[34:37], v[158:161], v[198:201], v[34:37]
	v_mfma_f32_16x16x32_bf16 v[26:29], v[150:153], v[224:227], v[26:29]
	v_mfma_f32_16x16x32_bf16 v[18:21], v[158:161], v[224:227], v[18:21]
	v_mfma_f32_16x16x32_bf16 v[10:13], v[150:153], v[232:235], v[10:13]
	v_mfma_f32_16x16x32_bf16 v[2:5], v[158:161], v[232:235], v[2:5]
	s_setprio 0
	s_barrier
; #define PG8_STAGE(bufoff, gbase, voff) do { _Pragma("unroll") for (int _i = 0; _i < 2; ++_i) \
;         __builtin_amdgcn_global_load_lds((const unsigned*)((const char*)(gbase) + (voff)[_i]), (LAS unsigned*)(lds + (bufoff) + ldsw + _i * 8192), 16, 0, 0); } while (0)
; #define PG8_LDA(dst, b, h) do { _Pragma("unroll") for (int m = 0; m < 4; ++m) _Pragma("unroll") for (int k = 0; k < 2; ++k) dst[m][k] = *(const LAS bf16x8*)(lds + PG8_SA(b, h) + aoff + m * 2048 + k * 1024); } while (0)
; #define PG8_LDB(dst, b, h) do { _Pragma("unroll") for (int n = 0; n < 2; ++n) _Pragma("unroll") for (int k = 0; k < 2; ++k) dst[n][k] = *(const LAS bf16x8*)(lds + PG8_SB(b, h) + boff + n * 2048 + k * 1024); } while (0)
; #define PG8_MMA(ai, bj, At, Bt) do { __builtin_amdgcn_s_setprio(1); _Pragma("unroll") for (int m = 0; m < 4; ++m) _Pragma("unroll") for (int n = 0; n < 2; ++n) _Pragma("unroll") for (int k = 0; k < 2; ++k) \
;         acc[ai][bj][m][n] = __builtin_amdgcn_mfma_f32_16x16x32_bf16(Bt[n][k], At[m][k], acc[ai][bj][m][n], 0, 0, 0); __builtin_amdgcn_s_setprio(0); } while (0)
; #define PG8_WAIT_V(n) asm volatile("s_waitcnt vmcnt(" #n ")" ::: "memory")
; #define PG8_WAIT_L(n) asm volatile("s_waitcnt lgkmcnt(" #n ")" ::: "memory")
; #define PG8_BAR __builtin_amdgcn_s_barrier()
; #define PG8_SCHED __builtin_amdgcn_sched_barrier(0)
; template <class Epi, class Sched>
; __device__ __forceinline__ void gemm_phase(LAS unsigned char* lds, const Gemm g, const Sched& S, const Epi& E) {
;     ...
;             PG8_LDB(B0, 1, 0); PG8_LDB(B1, 1, 1); PG8_SCHED; PG8_LDA(At, 1, 0); PG8_STAGE(PG8_SA(0, 1), a2 + hstepA, voffA);
;             PG8_WAIT_V(8); PG8_WAIT_L(0); PG8_BAR; PG8_MMA(0, 0, At, B0); PG8_MMA(0, 1, At, B1); PG8_BAR; PG8_SCHED;
;             PG8_LDA(At, 1, 1); PG8_STAGE(PG8_SB(1, 0), b3, voffB); PG8_STAGE(PG8_SB(1, 1), b3 + hstepB, voffB); PG8_STAGE(PG8_SA(1, 0), a3, voffA);
;             PG8_WAIT_V(8); PG8_WAIT_L(0); PG8_BAR; PG8_MMA(1, 0, At, B0); PG8_MMA(1, 1, At, B1); PG8_BAR; PG8_SCHED;
;         }
	s_add_i32 s88, 0, 0x18000
	s_add_i32 s89, 0, 0x1c000
	ds_read_b128 v[130:133], v246 offset:32768
	ds_read_b128 v[134:137], v246 offset:33792
	ds_read_b128 v[138:141], v246 offset:34816
	ds_read_b128 v[142:145], v246 offset:35840
	ds_read_b128 v[146:149], v246 offset:49152
	ds_read_b128 v[150:153], v246 offset:50176
	ds_read_b128 v[154:157], v246 offset:51200
	ds_read_b128 v[158:161], v246 offset:52224
	s_add_u32 s20, s20, 0x40000
	s_addc_u32 s21, s21, 0
	s_mov_b32 m0, s29
	ds_read_b128 v[162:165], v222 offset:32768
	ds_read_b128 v[166:169], v222 offset:33792
	ds_read_b128 v[194:197], v222 offset:34816
	ds_read_b128 v[198:201], v222 offset:35840
	ds_read_b128 v[202:205], v222 offset:36864
	ds_read_b128 v[224:227], v222 offset:37888
	ds_read_b128 v[228:231], v222 offset:38912
	ds_read_b128 v[232:235], v222 offset:39936
	global_load_lds_dwordx4 v170, s[20:21]
	s_mov_b32 m0, s30
	s_nop 0
	global_load_lds_dwordx4 v190, s[20:21]
	s_waitcnt vmcnt(8)
	s_waitcnt lgkmcnt(0)
	s_barrier
	s_setprio 1
	s_waitcnt lgkmcnt(0)
	v_mfma_f32_16x16x32_bf16 v[126:129], v[130:133], v[162:165], v[126:129]
	v_mfma_f32_16x16x32_bf16 v[118:121], v[138:141], v[162:165], v[118:121]
	v_mfma_f32_16x16x32_bf16 v[110:113], v[130:133], v[194:197], v[110:113]
	v_mfma_f32_16x16x32_bf16 v[102:105], v[138:141], v[194:197], v[102:105]
	v_mfma_f32_16x16x32_bf16 v[94:97], v[130:133], v[202:205], v[94:97]
	v_mfma_f32_16x16x32_bf16 v[86:89], v[138:141], v[202:205], v[86:89]
	v_mfma_f32_16x16x32_bf16 v[78:81], v[130:133], v[228:231], v[78:81]
	v_mfma_f32_16x16x32_bf16 v[70:73], v[138:141], v[228:231], v[70:73]
	v_mfma_f32_16x16x32_bf16 v[126:129], v[134:137], v[166:169], v[126:129]
	v_mfma_f32_16x16x32_bf16 v[118:121], v[142:145], v[166:169], v[118:121]
	v_mfma_f32_16x16x32_bf16 v[110:113], v[134:137], v[198:201], v[110:113]
	v_mfma_f32_16x16x32_bf16 v[102:105], v[142:145], v[198:201], v[102:105]
	v_mfma_f32_16x16x32_bf16 v[94:97], v[134:137], v[224:227], v[94:97]
	v_mfma_f32_16x16x32_bf16 v[86:89], v[142:145], v[224:227], v[86:89]
	v_mfma_f32_16x16x32_bf16 v[78:81], v[134:137], v[232:235], v[78:81]
	v_mfma_f32_16x16x32_bf16 v[70:73], v[142:145], v[232:235], v[70:73]
	s_setprio 0
	s_setprio 1
	v_mfma_f32_16x16x32_bf16 v[122:125], v[146:149], v[162:165], v[122:125]
	v_mfma_f32_16x16x32_bf16 v[114:117], v[154:157], v[162:165], v[114:117]
	v_mfma_f32_16x16x32_bf16 v[106:109], v[146:149], v[194:197], v[106:109]
	v_mfma_f32_16x16x32_bf16 v[98:101], v[154:157], v[194:197], v[98:101]
	v_mfma_f32_16x16x32_bf16 v[90:93], v[146:149], v[202:205], v[90:93]
	v_mfma_f32_16x16x32_bf16 v[82:85], v[154:157], v[202:205], v[82:85]
	v_mfma_f32_16x16x32_bf16 v[74:77], v[146:149], v[228:231], v[74:77]
	v_mfma_f32_16x16x32_bf16 v[66:69], v[154:157], v[228:231], v[66:69]
	v_mfma_f32_16x16x32_bf16 v[122:125], v[150:153], v[166:169], v[122:125]
	v_mfma_f32_16x16x32_bf16 v[114:117], v[158:161], v[166:169], v[114:117]
	v_mfma_f32_16x16x32_bf16 v[106:109], v[150:153], v[198:201], v[106:109]
	v_mfma_f32_16x16x32_bf16 v[98:101], v[158:161], v[198:201], v[98:101]
	v_mfma_f32_16x16x32_bf16 v[90:93], v[150:153], v[224:227], v[90:93]
	v_mfma_f32_16x16x32_bf16 v[82:85], v[158:161], v[224:227], v[82:85]
	v_mfma_f32_16x16x32_bf16 v[74:77], v[150:153], v[232:235], v[74:77]
	v_mfma_f32_16x16x32_bf16 v[66:69], v[158:161], v[232:235], v[66:69]
	s_setprio 0
	s_barrier
	s_add_i32 s20, s8, 0x18000
	s_add_u32 s88, s86, 0x80
	s_addc_u32 s89, s87, 0
	s_mov_b32 m0, s20
	ds_read_b128 v[162:165], v222 offset:49152
	ds_read_b128 v[166:169], v222 offset:50176
	ds_read_b128 v[194:197], v222 offset:51200
	ds_read_b128 v[198:201], v222 offset:52224
	ds_read_b128 v[202:205], v222 offset:53248
	ds_read_b128 v[224:227], v222 offset:54272
	ds_read_b128 v[228:231], v222 offset:55296
	ds_read_b128 v[232:235], v222 offset:56320
	global_load_lds_dwordx4 v172, s[88:89]
	s_add_i32 m0, s20, 0x2000
	s_add_u32 s20, s86, 0x40080
	s_addc_u32 s21, s87, 0
	s_add_i32 s12, s8, 0x1c000
	global_load_lds_dwordx4 v192, s[88:89]
	s_mov_b32 m0, s12
	s_nop 0
	global_load_lds_dwordx4 v172, s[20:21]
	s_add_i32 m0, s12, 0x2000
	s_nop 0
	global_load_lds_dwordx4 v192, s[20:21]
	s_mov_b32 m0, s31
	s_nop 0
	global_load_lds_dwordx4 v170, s[100:101]
	s_mov_b32 m0, s34
	s_nop 0
	global_load_lds_dwordx4 v190, s[100:101]
	s_waitcnt vmcnt(8)
	s_waitcnt lgkmcnt(0)
	s_barrier
	s_setprio 1
	s_waitcnt lgkmcnt(0)
	v_mfma_f32_16x16x32_bf16 v[62:65], v[130:133], v[162:165], v[62:65]
	v_mfma_f32_16x16x32_bf16 v[54:57], v[138:141], v[162:165], v[54:57]
	v_mfma_f32_16x16x32_bf16 v[46:49], v[130:133], v[194:197], v[46:49]
	v_mfma_f32_16x16x32_bf16 v[38:41], v[138:141], v[194:197], v[38:41]
	v_mfma_f32_16x16x32_bf16 v[30:33], v[130:133], v[202:205], v[30:33]
	v_mfma_f32_16x16x32_bf16 v[22:25], v[138:141], v[202:205], v[22:25]
	v_mfma_f32_16x16x32_bf16 v[14:17], v[130:133], v[228:231], v[14:17]
	v_mfma_f32_16x16x32_bf16 v[6:9], v[138:141], v[228:231], v[6:9]
	v_mfma_f32_16x16x32_bf16 v[62:65], v[134:137], v[166:169], v[62:65]
	v_mfma_f32_16x16x32_bf16 v[54:57], v[142:145], v[166:169], v[54:57]
	v_mfma_f32_16x16x32_bf16 v[46:49], v[134:137], v[198:201], v[46:49]
	v_mfma_f32_16x16x32_bf16 v[38:41], v[142:145], v[198:201], v[38:41]
	v_mfma_f32_16x16x32_bf16 v[30:33], v[134:137], v[224:227], v[30:33]
	v_mfma_f32_16x16x32_bf16 v[22:25], v[142:145], v[224:227], v[22:25]
	v_mfma_f32_16x16x32_bf16 v[14:17], v[134:137], v[232:235], v[14:17]
	v_mfma_f32_16x16x32_bf16 v[6:9], v[142:145], v[232:235], v[6:9]
	s_setprio 0
	s_setprio 1
	v_mfma_f32_16x16x32_bf16 v[58:61], v[146:149], v[162:165], v[58:61]
	v_mfma_f32_16x16x32_bf16 v[50:53], v[154:157], v[162:165], v[50:53]
	v_mfma_f32_16x16x32_bf16 v[42:45], v[146:149], v[194:197], v[42:45]
	v_mfma_f32_16x16x32_bf16 v[34:37], v[154:157], v[194:197], v[34:37]
	v_mfma_f32_16x16x32_bf16 v[26:29], v[146:149], v[202:205], v[26:29]
	v_mfma_f32_16x16x32_bf16 v[18:21], v[154:157], v[202:205], v[18:21]
	v_mfma_f32_16x16x32_bf16 v[10:13], v[146:149], v[228:231], v[10:13]
	v_mfma_f32_16x16x32_bf16 v[2:5], v[154:157], v[228:231], v[2:5]
	v_mfma_f32_16x16x32_bf16 v[58:61], v[150:153], v[166:169], v[58:61]
	v_mfma_f32_16x16x32_bf16 v[50:53], v[158:161], v[166:169], v[50:53]
	v_mfma_f32_16x16x32_bf16 v[42:45], v[150:153], v[198:201], v[42:45]
	v_mfma_f32_16x16x32_bf16 v[34:37], v[158:161], v[198:201], v[34:37]
	v_mfma_f32_16x16x32_bf16 v[26:29], v[150:153], v[224:227], v[26:29]
	v_mfma_f32_16x16x32_bf16 v[18:21], v[158:161], v[224:227], v[18:21]
	v_mfma_f32_16x16x32_bf16 v[10:13], v[150:153], v[232:235], v[10:13]
	v_mfma_f32_16x16x32_bf16 v[2:5], v[158:161], v[232:235], v[2:5]
	s_setprio 0
	s_barrier
	s_add_i32 s83, s83, 2
	s_add_u32 s18, s18, 0x100
	s_addc_u32 s19, s19, 0
	s_add_u32 s54, s54, 0x100
	s_addc_u32 s81, s81, 0
	s_cmp_gt_u32 s83, 13
	s_cbranch_scc0 .LBB0_232
	s_and_b64 vcc, exec, s[72:73]
	s_cbranch_vccz .LBB0_235
	s_barrier
